# v18 + deal rotations of the down / gate / gMLP-in phases aligned to XCD (32-workgroup) boundaries
# baseline (speedup 1.0000x reference)
; #define ORDER(S, nN, startu, ready, need, donec) pg8::ChainOrder S; S.init((nN), G, ROT(startu), (ready), (need), (donec), tmo, wave)
;     __device__ __forceinline__ bool next(int i, Unit& u) const {
;         if (team) { u.pm = tpm; u.pn = tj + i * tT; return u.pn < nN; }
;         const int L = i * G + c; if (L >= nwg) return false;
;         if (rowmajor == 2) { u.pm = 0; u.pn = 0; return true; }
;         if (rowmajor) { u.pm = L / nN; u.pn = L % nN; return true; }
;         const int pg = L / (4 * nN), r = L % (4 * nN); u.pm = 4 * pg + (r & 3); u.pn = r >> 2; return true; }
; __global__ void __launch_bounds__(NWAVES * 64, 2) mk_fwd(Args args) {
;     ...
;     if (IN(6)) {
;         { pg8::Gemm g{ACT, (const bf16*)(ws + WS_WDN0), MROWS, DM, DFF / 2, DFF}; ORDER(S, NT, U_WO + U_UP + U_CONV, CNT(6), 8u, CNT(12)); S.wslot = 3;
.LBB0_495:
	s_cmp_gt_i32 s58, 6
	s_cselect_b64 s[0:1], -1, 0
	s_cmp_lt_i32 s59, 7
	s_cselect_b64 s[2:3], -1, 0
	s_or_b64 s[0:1], s[0:1], s[2:3]
	s_and_b64 vcc, exec, s[0:1]
	v_writelane_b32 v249, s82, 5
	s_cbranch_vccnz .LBB0_649
	s_abs_i32 s17, s82
	v_cvt_f32_u32_e32 v0, s17
	s_sub_i32 s2, 0, s17
	s_add_i32 s0, s60, 0xfffff880
	s_ashr_i32 s1, s0, 31
	v_rcp_iflag_f32_e32 v0, v0
	s_abs_i32 s0, s0
	v_mbcnt_hi_u32_b32 v148, -1, v234
	v_mov_b32_e32 v8, v148
	v_mul_f32_e32 v0, 0x4f7ffffe, v0
	v_cvt_u32_f32_e32 v0, v0
	s_nop 0
	v_readfirstlane_b32 s3, v0
	s_mul_i32 s2, s2, s3
	s_mul_hi_u32 s2, s3, s2
	s_add_i32 s49, s3, s2
	s_mul_hi_u32 s2, s0, s49
	s_mul_i32 s2, s2, s17
	s_sub_i32 s0, s0, s2
	s_sub_i32 s2, s0, s17
	s_cmp_ge_u32 s0, s17
	s_cselect_b32 s0, s2, s0
	s_sub_i32 s2, s0, s17
	s_cmp_ge_u32 s0, s17
	s_cselect_b32 s0, s2, s0
	s_xor_b32 s0, s0, s1
	s_sub_i32 s0, s0, s1
	s_add_i32 s0, s0, s82
	s_ashr_i32 s1, s0, 31
	s_abs_i32 s0, s0
	s_mul_hi_u32 s2, s0, s49
	s_mul_i32 s2, s2, s17
	s_sub_i32 s0, s0, s2
	s_sub_i32 s2, s0, s17
	s_cmp_ge_u32 s0, s17
	s_cselect_b32 s0, s2, s0
	s_sub_i32 s2, s0, s17
	s_cmp_ge_u32 s0, s17
	s_cselect_b32 s0, s2, s0
	s_xor_b32 s0, s0, s1
	s_sub_i32 s80, s0, s1
	s_cmpk_lt_i32 s80, 0x120
	s_cselect_b64 s[0:1], -1, 0
	s_cmpk_gt_i32 s80, 0x11f
	s_cbranch_scc1 .LBB0_498
	s_ashr_i32 s2, s80, 31
	s_lshr_b32 s2, s2, 27
	s_add_i32 s2, s80, s2
	s_ashr_i32 s3, s2, 5
	s_andn2_b32 s2, s2, 31
	s_sub_i32 s2, s80, s2
	s_lshl_b32 s3, s3, 2
	s_and_b32 s4, s2, 3
	s_or_b32 s68, s4, s3
	s_ashr_i32 s81, s2, 2

; #define ORDER(S, nN, startu, ready, need, donec) pg8::ChainOrder S; S.init((nN), G, ROT(startu), (ready), (need), (donec), tmo, wave)
;     __device__ __forceinline__ bool next(int i, Unit& u) const {
;         if (team) { u.pm = tpm; u.pn = tj + i * tT; return u.pn < nN; }
;         const int L = i * G + c; if (L >= nwg) return false;
;         if (rowmajor == 2) { u.pm = 0; u.pn = 0; return true; }
;         if (rowmajor) { u.pm = L / nN; u.pn = L % nN; return true; }
;         const int pg = L / (4 * nN), r = L % (4 * nN); u.pm = 4 * pg + (r & 3); u.pn = r >> 2; return true; }
; __global__ void __launch_bounds__(NWAVES * 64, 2) mk_fwd(Args args) {
;     ...
;         { pg8::Gemm g{ACT + DFF / 2, (const bf16*)(ws + WS_WDN0) + DFF / 2, MROWS, DM, DFF / 2, DFF}; ORDER(S, NT, 2 * U_WO + U_UP + U_CONV, CNT(6), 8u, CNT(1)); S.eready = CNT(12); S.eneed = 8u * NT; S.wslot = 4;
.LBB0_558:
	s_add_i32 s0, s60, 0xfffff760
	s_ashr_i32 s1, s0, 31
	s_abs_i32 s0, s0
	s_mul_hi_u32 s2, s0, s49
	s_mul_i32 s2, s2, s17
	s_sub_i32 s0, s0, s2
	s_sub_i32 s2, s0, s17
	s_cmp_ge_u32 s0, s17
	s_cselect_b32 s0, s2, s0
	s_sub_i32 s2, s0, s17
	s_cmp_ge_u32 s0, s17
	s_cselect_b32 s0, s2, s0
	s_xor_b32 s0, s0, s1
	s_sub_i32 s0, s0, s1
	s_add_i32 s0, s0, s82
	s_ashr_i32 s1, s0, 31
	s_abs_i32 s0, s0
	s_mul_hi_u32 s2, s0, s49
	s_mul_i32 s2, s2, s17
	s_sub_i32 s0, s0, s2
	s_sub_i32 s2, s0, s17
	s_cmp_ge_u32 s0, s17
	s_cselect_b32 s0, s2, s0
	s_sub_i32 s2, s0, s17
	s_cmp_ge_u32 s0, s17
	s_cselect_b32 s0, s2, s0
	s_xor_b32 s0, s0, s1
	s_sub_i32 s17, s0, s1
	s_cmpk_lt_i32 s17, 0x120
	v_mov_b32_e32 v8, v148
	s_cselect_b64 s[0:1], -1, 0
	s_cmpk_gt_i32 s17, 0x11f
	s_cbranch_scc1 .LBB0_560
	s_ashr_i32 s2, s17, 31
	s_lshr_b32 s2, s2, 27
	s_add_i32 s2, s17, s2
	s_ashr_i32 s3, s2, 5
	s_andn2_b32 s2, s2, 31
	s_sub_i32 s2, s17, s2
	s_lshl_b32 s3, s3, 2
	s_and_b32 s4, s2, 3
	s_or_b32 s67, s4, s3
	s_ashr_i32 s90, s2, 2

; #define PG8_STAGE(bufoff, gbase, voff) do { _Pragma("unroll") for (int _i = 0; _i < 2; ++_i) \
;         __builtin_amdgcn_global_load_lds((const unsigned*)((const char*)(gbase) + (voff)[_i]), (PG8_LAS unsigned*)(lds + (bufoff) + ldsw + _i * 8192), 16, 0, 0); } while (0)
; #define PG8_BAR __builtin_amdgcn_s_barrier()
; template <class Epi, class Sched, bool ALIGN_EPI = false, bool SP2 = false, bool APERM = false  >
; __device__ __forceinline__ void gemm_phase(PG8_LAS unsigned char* lds, const Gemm g, const Sched& S, const Epi& E, const int wid  ) {
;     ...
;     for (int i = 0; i < 2; ++i) { int R, C; stage_rc(tid * 16 + i * 8192, R, C); const int Rb = Epi::PERM ? ((R & ~31) + perm32(R & 31)) : R;
;         const int Ra = APERM ? ((R & ~63) | ((R & 15) << 2) | ((R >> 4) & 3)) : R;
;         voffA[i] = (unsigned)(Ra * LDP + C) * 2u; voffB[i] = (unsigned)(Rb * LDP + C) * 2u; }
;     const size_t kstep = (size_t)(BK * 2);
;     const size_t hstep = (size_t)HALF * LDP * 2;
;     const size_t tstep = 2 * hstep;
;     const unsigned ldsw = (unsigned)wid * 1024u;
;     const int aoff = lds_byte(wr * 64 + fr, fq * 8), boff = lds_byte(wc * 32 + fr, fq * 8);
;     ...
;     Unit cur, nxt; int ui = 0;
;     if (!S.next(0, cur)) return;
;     f32x4 acc[2][2][4][2];
; #pragma unroll
;     for (int a = 0; a < 2; ++a)
; #pragma unroll
;         for (int b = 0; b < 2; ++b)
; #pragma unroll
;             for (int m = 0; m < 4; ++m)
; #pragma unroll
;                 for (int n = 0; n < 2; ++n) acc[a][b][m][n] = (f32x4){0.f, 0.f, 0.f, 0.f};
;     bf16x8 At[4][2], B0[2][2], B1[2][2];
;     const char* cA = (const char*)g.A + (size_t)cur.pm * tstep; const char* cB = (const char*)g.Bt + (size_t)cur.pn * tstep;
;     if constexpr (SP2) {
;         PG8_STAGE(PG8_SB(0, 0), cB, voffB); PG8_STAGE(PG8_SB(0, 1), cB + hstep, voffB);
;         S.a_ready(cur);
;         PG8_STAGE(PG8_SA(0, 0), cA, voffA); PG8_STAGE(PG8_SA(0, 1), cA + hstep, voffA);
;         if (wr == 1) PG8_BAR;
;         PG8_WAIT_V(2); PG8_BAR;
;         PG8_STAGE(PG8_SB(1, 0), cB + kstep, voffB); PG8_STAGE(PG8_SA(1, 0), cA + kstep, voffA); PG8_STAGE(PG8_SB(1, 1), cB + hstep + kstep, voffB);
; __global__ void __launch_bounds__(NWAVES * 64, 2) mk_fwd(Args args) {
;     ...
;     if (IN(7)) { pg8::Gemm g{PB, (const bf16*)(ws + WS_WP0), MROWS, DM, kple, kple}; ORDER(S, NT, 3 * U_WO + U_UP + U_CONV, nullptr, 0u, nullptr);
.LBB0_649:
	s_movk_i32 s0, 0x100
	s_cmp_gt_i32 s58, 7
	v_writelane_b32 v249, s0, 17
	s_nop 1
	v_writelane_b32 v249, s1, 18
	s_cselect_b64 s[0:1], -1, 0
	s_cmp_lt_i32 s59, 8
	s_cselect_b64 s[2:3], -1, 0
	s_or_b64 s[0:1], s[0:1], s[2:3]
	s_and_b64 vcc, exec, s[0:1]
	s_cbranch_vccnz .LBB0_742
	s_add_u32 s8, s22, 0x2d500000
	s_addc_u32 s9, s23, 0
	s_abs_i32 s0, s82
	v_cvt_f32_u32_e32 v0, s0
	s_sub_i32 s3, 0, s0
	s_add_i32 s1, s60, 0xfffff640
	s_ashr_i32 s2, s1, 31
	v_rcp_iflag_f32_e32 v0, v0
	s_abs_i32 s1, s1
	v_mbcnt_hi_u32_b32 v150, -1, v234
	v_mov_b32_e32 v1, v150
	v_mul_f32_e32 v0, 0x4f7ffffe, v0
	v_cvt_u32_f32_e32 v0, v0
	s_nop 0
	v_readfirstlane_b32 s4, v0
	s_mul_i32 s3, s3, s4
	s_mul_hi_u32 s3, s4, s3
	s_add_i32 s4, s4, s3
	s_mul_hi_u32 s3, s1, s4
	s_mul_i32 s3, s3, s0
	s_sub_i32 s1, s1, s3
	s_sub_i32 s3, s1, s0
	s_cmp_ge_u32 s1, s0
	s_cselect_b32 s1, s3, s1
	s_sub_i32 s3, s1, s0
	s_cmp_ge_u32 s1, s0
	s_cselect_b32 s1, s3, s1
	s_xor_b32 s1, s1, s2
	s_sub_i32 s1, s1, s2
	s_add_i32 s1, s1, s82
	s_ashr_i32 s2, s1, 31
	s_abs_i32 s1, s1
	s_mul_hi_u32 s3, s1, s4
	s_mul_i32 s3, s3, s0
	s_sub_i32 s1, s1, s3
	s_sub_i32 s3, s1, s0
	s_cmp_ge_u32 s1, s0
	s_cselect_b32 s1, s3, s1
	s_sub_i32 s3, s1, s0
	s_cmp_ge_u32 s1, s0
	s_cselect_b32 s0, s3, s1
	v_readlane_b32 s1, v250, 8
	s_xor_b32 s0, s0, s2
	s_sub_i32 s47, s0, s2
	s_lshl_b32 s0, s1, 5
	s_lshr_b32 s58, s63, 8
	s_and_b32 s33, s0, 0x60
	s_lshl_b32 s46, s1, 10
	s_lshl_b32 s62, s58, 6
	s_lshl_b32 s53, s58, 13
	s_lshr_b32 s52, s33, 3
	s_cmpk_lt_i32 s47, 0x120
	s_cselect_b64 s[2:3], -1, 0
	s_cmpk_gt_i32 s47, 0x11f
	s_cbranch_scc1 .LBB0_672
	v_lshl_add_u32 v0, v1, 4, s46
	v_add_u32_e32 v2, 0x2000, v0
	v_ashrrev_i32_e32 v3, 31, v2
	v_lshrrev_b32_e32 v3, 22, v3
	v_add_u32_e32 v3, v2, v3
	v_ashrrev_i32_e32 v3, 10, v3
	v_mul_i32_i24_e32 v4, 0x400, v3
	v_sub_u32_e32 v2, v2, v4
	v_lshrrev_b32_e32 v4, 4, v2
	v_bitop3_b32 v2, v4, v2, 32 bitop3:0x6c
	v_ashrrev_i32_e32 v4, 31, v2
	v_lshrrev_b32_e32 v4, 26, v4
	v_add_u32_e32 v4, v2, v4
	v_lshlrev_b32_e32 v6, 3, v3
	v_lshlrev_b32_e32 v3, 5, v3
	v_and_b32_e32 v14, 32, v3
	v_and_b32_e32 v3, 0xffc0, v4
	v_sub_u32_e32 v2, v2, v3
	v_ashrrev_i32_e32 v5, 6, v4
	v_and_b32_e32 v6, -16, v6
	v_lshrrev_b16_e32 v3, 7, v2
	v_add_u32_e32 v6, v5, v6
	v_and_b32_e32 v3, 1, v3
	v_and_b32_e32 v5, 3, v5
	s_mov_b32 s0, 0x7fffffe0
	v_lshrrev_b32_e32 v7, 2, v6
	v_lshlrev_b32_e32 v8, 1, v6
	v_add_u16_e32 v2, v2, v3
	v_mov_b32_e32 v3, 1
	v_and_or_b32 v5, v6, s0, v5
	v_and_b32_e32 v7, 4, v7
	v_and_b32_e32 v8, 24, v8
	v_ashrrev_i16_sdwa v2, v3, sext(v2) dst_sel:DWORD dst_unused:UNUSED_PAD src0_sel:DWORD src1_sel:BYTE_0
	v_readlane_b32 s18, v249, 17
	v_or3_b32 v5, v5, v7, v8
	v_bfe_i32 v15, v2, 0, 16
	v_mul_lo_u32 v5, v5, s18
	v_add_u32_e32 v2, v14, v15
	s_waitcnt vmcnt(15)
	v_mul_lo_u32 v16, v6, s18
	v_add_lshl_u32 v132, v5, v2, 1
	v_add_lshl_u32 v134, v2, v16, 1
	v_ashrrev_i32_e32 v2, 31, v0
	v_lshrrev_b32_e32 v2, 22, v2
	v_add_u32_e32 v2, v0, v2
	v_ashrrev_i32_e32 v2, 10, v2
	v_mul_i32_i24_e32 v4, 0x400, v2
	v_sub_u32_e32 v0, v0, v4
	v_lshrrev_b32_e32 v4, 4, v0
	v_bitop3_b32 v0, v4, v0, 32 bitop3:0x6c
	v_ashrrev_i32_e32 v4, 31, v0
	v_lshrrev_b32_e32 v4, 26, v4
	v_add_u32_e32 v4, v0, v4
	v_lshlrev_b32_e32 v6, 3, v2
	v_ashrrev_i32_e32 v5, 6, v4
	v_and_b32_e32 v6, -16, v6
	s_add_u32 s56, s22, 0xd000000
	v_add_u32_e32 v6, v5, v6
	v_and_b32_e32 v5, 3, v5
	s_addc_u32 s57, s23, 0
	v_and_or_b32 v5, v6, s0, v5
	s_ashr_i32 s0, s47, 31
	s_lshr_b32 s0, s0, 27
	s_add_i32 s0, s47, s0
	s_and_b32 s1, s0, 0xffffffe0
	v_readlane_b32 s19, v249, 18
	s_sub_i32 s1, s47, s1
	s_ashr_i32 s0, s0, 5
	s_ashr_i32 s19, s18, 31
	s_lshl_b32 s10, s0, 2
	s_and_b32 s11, s1, 3
	s_lshl_b64 s[6:7], s[18:19], 9
	s_or_b32 s61, s11, s10
	s_ashr_i32 s0, s0, 31
	s_ashr_i32 s60, s1, 2
	s_mul_hi_u32 s1, s6, s61
	s_mul_i32 s0, s6, s0
	s_add_i32 s10, s1, s0
	s_lshr_b64 s[0:1], s[18:19], 23
	s_mul_i32 s1, s0, s61
	v_lshlrev_b32_e32 v2, 5, v2
	s_add_i32 s12, s10, s1
	s_ashr_i32 s1, s60, 31
	v_and_b32_e32 v17, 32, v2
	v_and_b32_e32 v2, 0xc0, v4
	s_mul_hi_u32 s10, s6, s60
	s_mul_i32 s1, s6, s1
	v_lshrrev_b32_e32 v7, 2, v6
	v_lshlrev_b32_e32 v8, 1, v6
	v_sub_u32_e32 v0, v0, v2
	s_add_i32 s1, s10, s1
	s_mul_i32 s0, s0, s60
	s_lshl_b64 s[4:5], s[18:19], 8
	v_and_b32_e32 v7, 4, v7
	v_and_b32_e32 v8, 24, v8
	v_ashrrev_i16_sdwa v0, v3, sext(v0) dst_sel:DWORD dst_unused:UNUSED_PAD src0_sel:DWORD src1_sel:BYTE_0
	s_add_i32 s1, s1, s0
	s_mul_i32 s0, s6, s60
	v_or3_b32 v5, v5, v7, v8
	v_bfe_i32 v18, v0, 0, 16
	s_add_u32 s10, s56, s0
	v_mul_lo_u32 v5, v5, s18
	v_add_u32_e32 v0, v17, v18
	s_addc_u32 s11, s57, s1
	s_add_i32 s59, s46, 0
	v_add_lshl_u32 v136, v5, v0, 1
	s_add_i32 m0, s59, 0x10000
	s_mul_i32 s13, s6, s61
	global_load_lds_dwordx4 v136, s[10:11]
	s_add_i32 m0, s59, 0x12000
	s_add_u32 s0, s10, s4
	global_load_lds_dwordx4 v132, s[10:11]
	s_addc_u32 s1, s11, s5
	s_add_i32 m0, s59, 0x14000
	v_mul_lo_u32 v19, v6, s18
	global_load_lds_dwordx4 v136, s[0:1]
	s_add_i32 m0, s59, 0x16000
	s_add_u32 s14, s92, s13
	s_addc_u32 s15, s93, s12
	s_add_i32 s63, s59, 0x2000
	v_add_lshl_u32 v138, v0, v19, 1
	global_load_lds_dwordx4 v132, s[0:1]
	s_mov_b32 m0, s59
	s_add_u32 s12, s14, s4
	global_load_lds_dwordx4 v138, s[14:15]
	s_mov_b32 m0, s63
	s_addc_u32 s13, s15, s5
	s_add_i32 s64, s59, 0x4000
	global_load_lds_dwordx4 v134, s[14:15]
	s_mov_b32 m0, s64
	s_add_i32 s65, s59, 0x6000
	global_load_lds_dwordx4 v138, s[12:13]
	s_mov_b32 m0, s65
	v_mov_b32_e32 v0, 0
	global_load_lds_dwordx4 v134, s[12:13]
	v_mov_b32_e32 v137, v0
	v_mov_b32_e32 v133, v0
	v_mov_b32_e32 v139, v0
	v_mov_b32_e32 v135, v0
	s_cmp_eq_u32 s58, 1
	v_lshl_add_u64 v[10:11], s[10:11], 0, v[136:137]
	v_lshl_add_u64 v[6:7], s[10:11], 0, v[132:133]
	v_lshl_add_u64 v[4:5], s[0:1], 0, v[136:137]
	v_lshl_add_u64 v[2:3], s[0:1], 0, v[132:133]
	v_lshl_add_u64 v[8:9], s[14:15], 0, v[138:139]
	s_cselect_b64 s[12:13], -1, 0
	s_cmp_lg_u32 s58, 1
	v_lshl_add_u64 v[12:13], s[14:15], 0, v[134:135]
	s_cbranch_scc1 .LBB0_653
	s_barrier

; #define PG8_LAS __attribute__((address_space(3)))
; #define ORDER(S, nN, startu, ready, need, donec) pg8::ChainOrder S; S.init((nN), G, ROT(startu), (ready), (need), (donec), tmo, wave)
;     __device__ __forceinline__ bool next(int i, Unit& u) const {
;         if (team) { u.pm = tpm; u.pn = tj + i * tT; return u.pn < nN; }
;         const int L = i * G + c; if (L >= nwg) return false;
;         if (rowmajor == 2) { u.pm = 0; u.pn = 0; return true; }
;         if (rowmajor) { u.pm = L / nN; u.pn = L % nN; return true; }
;         const int pg = L / (4 * nN), r = L % (4 * nN); u.pm = 4 * pg + (r & 3); u.pn = r >> 2; return true; }
; __global__ void __launch_bounds__(NWAVES * 64, 2) mk_fwd(Args args) {
;     ...
;     if (IN(8)) { pg8::Gemm g{XB1, (const bf16*)(ws + WS_WIN), MROWS, 2 * DM, DM, DM}; ORDER(S, 2 * NT, 4 * U_WO + U_UP + U_CONV, CNT(2), 8u * NT, nullptr); S.wslot = 6; S.okflag = (PG8_LAS unsigned*)(MISC + 18);
.LBB0_742:
	s_add_u32 s8, s22, 0x32600000
	s_addc_u32 s9, s23, 0
	s_add_u32 s10, s22, 0x34a00000
	s_addc_u32 s11, s23, 0
	v_readlane_b32 s58, v250, 59
	s_cmp_lt_i32 s58, 9
	v_readlane_b32 s59, v250, 60
	s_cselect_b64 s[12:13], -1, 0
	s_cmp_gt_i32 s58, 8
	s_cselect_b64 s[0:1], -1, 0
	s_cmp_lt_i32 s59, 9
	s_cselect_b64 s[2:3], -1, 0
	v_readlane_b32 s36, v250, 41
	s_or_b64 s[0:1], s[0:1], s[2:3]
	v_readlane_b32 s48, v250, 53
	v_readlane_b32 s49, v250, 54
	s_and_b64 vcc, exec, s[0:1]
	s_mov_b64 s[64:65], s[48:49]
	v_readlane_b32 s37, v250, 42
	v_readlane_b32 s38, v250, 43
	v_readlane_b32 s39, v250, 44
	v_readlane_b32 s40, v250, 45
	v_readlane_b32 s41, v250, 46
	v_readlane_b32 s42, v250, 47
	v_readlane_b32 s43, v250, 48
	v_readlane_b32 s44, v250, 49
	v_readlane_b32 s45, v250, 50
	v_readlane_b32 s46, v250, 51
	v_readlane_b32 s47, v250, 52
	v_readlane_b32 s50, v250, 55
	v_readlane_b32 s51, v250, 56
	s_cbranch_vccnz .LBB0_860
	s_abs_i32 s0, s82
	v_cvt_f32_u32_e32 v0, s0
	s_sub_i32 s3, 0, s0
	s_add_i32 s1, s60, 0xfffff520
	s_ashr_i32 s2, s1, 31
	v_rcp_iflag_f32_e32 v0, v0
	s_abs_i32 s1, s1
	v_mbcnt_hi_u32_b32 v158, -1, v234
	v_mov_b32_e32 v8, v158
	v_mul_f32_e32 v0, 0x4f7ffffe, v0
	v_cvt_u32_f32_e32 v0, v0
	s_nop 0
	v_readfirstlane_b32 s4, v0
	s_mul_i32 s3, s3, s4
	s_mul_hi_u32 s3, s4, s3
	s_add_i32 s4, s4, s3
	s_mul_hi_u32 s3, s1, s4
	s_mul_i32 s3, s3, s0
	s_sub_i32 s1, s1, s3
	s_sub_i32 s3, s1, s0
	s_cmp_ge_u32 s1, s0
	s_cselect_b32 s1, s3, s1
	s_sub_i32 s3, s1, s0
	s_cmp_ge_u32 s1, s0
	s_cselect_b32 s1, s3, s1
	s_xor_b32 s1, s1, s2
	s_sub_i32 s1, s1, s2
	s_add_i32 s1, s1, s82
	s_ashr_i32 s2, s1, 31
	s_abs_i32 s1, s1
	s_mul_hi_u32 s3, s1, s4
	s_mul_i32 s3, s3, s0
	s_sub_i32 s1, s1, s3
	s_sub_i32 s3, s1, s0
	s_cmp_ge_u32 s1, s0
	s_cselect_b32 s1, s3, s1
	s_sub_i32 s3, s1, s0
	s_cmp_ge_u32 s1, s0
	s_cselect_b32 s0, s3, s1
	s_xor_b32 s0, s0, s2
	s_sub_i32 s26, s0, s2
	s_cmpk_lt_i32 s26, 0x240
	s_cselect_b64 s[0:1], -1, 0
	s_cmpk_gt_i32 s26, 0x23f
	s_cbranch_scc1 .LBB0_745
	s_ashr_i32 s2, s26, 31
	s_lshr_b32 s2, s2, 26
	s_add_i32 s2, s26, s2
	s_ashr_i32 s3, s2, 6
	s_andn2_b32 s2, s2, 63
	s_sub_i32 s2, s26, s2
	s_lshl_b32 s3, s3, 2
	s_and_b32 s4, s2, 3
	s_or_b32 s54, s4, s3
	s_ashr_i32 s14, s2, 2

; #define ORDER(S, nN, startu, ready, need, donec) pg8::ChainOrder S; S.init((nN), G, ROT(startu), (ready), (need), (donec), tmo, wave)
;     __device__ __forceinline__ bool next(int i, Unit& u) const {
;         if (team) { u.pm = tpm; u.pn = tj + i * tT; return u.pn < nN; }
;         const int L = i * G + c; if (L >= nwg) return false;
;         if (rowmajor == 2) { u.pm = 0; u.pn = 0; return true; }
;         if (rowmajor) { u.pm = L / nN; u.pn = L % nN; return true; }
;         const int pg = L / (4 * nN), r = L % (4 * nN); u.pm = 4 * pg + (r & 3); u.pn = r >> 2; return true; }
; __global__ void __launch_bounds__(NWAVES * 64, 2) mk_fwd(Args args) {
;     ...
;         { pg8::Gemm g{ACT, (const bf16*)(ws + WS_WDN1), MROWS, DM, DFF / 2, DFF}; ORDER(S, NT, U_WO + U_UP + U_CONV, CNT(8), 8u, CNT(13)); S.wslot = 3;
.LBB0_1204:
	s_cmp_gt_i32 s58, 13
	s_cselect_b64 s[0:1], -1, 0
	s_cmp_lt_i32 s59, 14
	s_cselect_b64 s[2:3], -1, 0
	s_or_b64 s[0:1], s[0:1], s[2:3]
	s_and_b64 vcc, exec, s[0:1]
	s_cbranch_vccnz .LBB0_1358
	v_readlane_b32 s3, v249, 5
	s_abs_i32 s80, s3
	v_cvt_f32_u32_e32 v0, s80
	s_sub_i32 s2, 0, s80
	s_add_i32 s0, s60, 0xfffff880
	s_ashr_i32 s1, s0, 31
	v_rcp_iflag_f32_e32 v0, v0
	s_abs_i32 s0, s0
	v_mbcnt_hi_u32_b32 v148, -1, v234
	v_mov_b32_e32 v8, v148
	v_mul_f32_e32 v0, 0x4f7ffffe, v0
	v_cvt_u32_f32_e32 v0, v0
	s_nop 0
	v_readfirstlane_b32 s81, v0
	s_mul_i32 s2, s2, s81
	s_mul_hi_u32 s2, s81, s2
	s_add_i32 s81, s81, s2
	s_mul_hi_u32 s2, s0, s81
	s_mul_i32 s2, s2, s80
	s_sub_i32 s0, s0, s2
	s_sub_i32 s2, s0, s80
	s_cmp_ge_u32 s0, s80
	s_cselect_b32 s0, s2, s0
	s_sub_i32 s2, s0, s80
	s_cmp_ge_u32 s0, s80
	s_cselect_b32 s0, s2, s0
	s_xor_b32 s0, s0, s1
	s_sub_i32 s0, s0, s1
	s_add_i32 s0, s0, s3
	s_ashr_i32 s1, s0, 31
	s_abs_i32 s0, s0
	s_mul_hi_u32 s2, s0, s81
	s_mul_i32 s2, s2, s80
	s_sub_i32 s0, s0, s2
	s_sub_i32 s2, s0, s80
	s_cmp_ge_u32 s0, s80
	s_cselect_b32 s0, s2, s0
	s_sub_i32 s2, s0, s80
	s_cmp_ge_u32 s0, s80
	s_cselect_b32 s0, s2, s0
	s_xor_b32 s0, s0, s1
	s_sub_i32 s82, s0, s1
	s_cmpk_lt_i32 s82, 0x120
	s_cselect_b64 s[0:1], -1, 0
	s_cmpk_gt_i32 s82, 0x11f
	s_cbranch_scc1 .LBB0_1207
	s_ashr_i32 s2, s82, 31
	s_lshr_b32 s2, s2, 27
	s_add_i32 s2, s82, s2
	s_ashr_i32 s3, s2, 5
	s_andn2_b32 s2, s2, 31
	s_sub_i32 s2, s82, s2
	s_lshl_b32 s3, s3, 2
	s_and_b32 s4, s2, 3
	s_or_b32 s76, s4, s3
	s_ashr_i32 s83, s2, 2

; #define ORDER(S, nN, startu, ready, need, donec) pg8::ChainOrder S; S.init((nN), G, ROT(startu), (ready), (need), (donec), tmo, wave)
;     __device__ __forceinline__ bool next(int i, Unit& u) const {
;         if (team) { u.pm = tpm; u.pn = tj + i * tT; return u.pn < nN; }
;         const int L = i * G + c; if (L >= nwg) return false;
;         if (rowmajor == 2) { u.pm = 0; u.pn = 0; return true; }
;         if (rowmajor) { u.pm = L / nN; u.pn = L % nN; return true; }
;         const int pg = L / (4 * nN), r = L % (4 * nN); u.pm = 4 * pg + (r & 3); u.pn = r >> 2; return true; }
; __global__ void __launch_bounds__(NWAVES * 64, 2) mk_fwd(Args args) {
;     ...
;         { pg8::Gemm g{ACT + DFF / 2, (const bf16*)(ws + WS_WDN1) + DFF / 2, MROWS, DM, DFF / 2, DFF}; ORDER(S, NT, 2 * U_WO + U_UP + U_CONV, CNT(8), 8u, CNT(4)); S.eready = CNT(13); S.eneed = 8u * NT; S.wslot = 4;
.LBB0_1267:
	s_add_i32 s0, s60, 0xfffff760
	s_ashr_i32 s1, s0, 31
	s_abs_i32 s0, s0
	s_mul_hi_u32 s2, s0, s81
	s_mul_i32 s2, s2, s80
	s_sub_i32 s0, s0, s2
	s_sub_i32 s2, s0, s80
	s_cmp_ge_u32 s0, s80
	s_cselect_b32 s0, s2, s0
	s_sub_i32 s2, s0, s80
	s_cmp_ge_u32 s0, s80
	s_cselect_b32 s0, s2, s0
	s_xor_b32 s0, s0, s1
	s_sub_i32 s0, s0, s1
	v_readlane_b32 s1, v249, 5
	s_add_i32 s0, s0, s1
	s_ashr_i32 s1, s0, 31
	s_abs_i32 s0, s0
	s_mul_hi_u32 s2, s0, s81
	s_mul_i32 s2, s2, s80
	s_sub_i32 s0, s0, s2
	s_sub_i32 s2, s0, s80
	s_cmp_ge_u32 s0, s80
	s_cselect_b32 s0, s2, s0
	s_sub_i32 s2, s0, s80
	s_cmp_ge_u32 s0, s80
	s_cselect_b32 s0, s2, s0
	s_xor_b32 s0, s0, s1
	s_sub_i32 s80, s0, s1
	s_cmpk_lt_i32 s80, 0x120
	v_mov_b32_e32 v8, v148
	s_cselect_b64 s[0:1], -1, 0
	s_cmpk_gt_i32 s80, 0x11f
	s_cbranch_scc1 .LBB0_1269
	s_ashr_i32 s2, s80, 31
	s_lshr_b32 s2, s2, 27
	s_add_i32 s2, s80, s2
	s_ashr_i32 s3, s2, 5
	s_andn2_b32 s2, s2, 31
	s_sub_i32 s2, s80, s2
	s_lshl_b32 s3, s3, 2
	s_and_b32 s4, s2, 3
	s_or_b32 s82, s4, s3
	s_ashr_i32 s81, s2, 2

; #define PG8_STAGE(bufoff, gbase, voff) do { _Pragma("unroll") for (int _i = 0; _i < 2; ++_i) \
;         __builtin_amdgcn_global_load_lds((const unsigned*)((const char*)(gbase) + (voff)[_i]), (PG8_LAS unsigned*)(lds + (bufoff) + ldsw + _i * 8192), 16, 0, 0); } while (0)
; #define PG8_BAR __builtin_amdgcn_s_barrier()
; template <class Epi, class Sched, bool ALIGN_EPI = false, bool SP2 = false, bool APERM = false  >
; __device__ __forceinline__ void gemm_phase(PG8_LAS unsigned char* lds, const Gemm g, const Sched& S, const Epi& E, const int wid  ) {
;     ...
;     for (int i = 0; i < 2; ++i) { int R, C; stage_rc(tid * 16 + i * 8192, R, C); const int Rb = Epi::PERM ? ((R & ~31) + perm32(R & 31)) : R;
;         const int Ra = APERM ? ((R & ~63) | ((R & 15) << 2) | ((R >> 4) & 3)) : R;
;         voffA[i] = (unsigned)(Ra * LDP + C) * 2u; voffB[i] = (unsigned)(Rb * LDP + C) * 2u; }
;     const size_t kstep = (size_t)(BK * 2);
;     const size_t hstep = (size_t)HALF * LDP * 2;
;     const size_t tstep = 2 * hstep;
;     const unsigned ldsw = (unsigned)wid * 1024u;
;     const int aoff = lds_byte(wr * 64 + fr, fq * 8), boff = lds_byte(wc * 32 + fr, fq * 8);
;     ...
;     Unit cur, nxt; int ui = 0;
;     if (!S.next(0, cur)) return;
;     f32x4 acc[2][2][4][2];
; #pragma unroll
;     for (int a = 0; a < 2; ++a)
; #pragma unroll
;         for (int b = 0; b < 2; ++b)
; #pragma unroll
;             for (int m = 0; m < 4; ++m)
; #pragma unroll
;                 for (int n = 0; n < 2; ++n) acc[a][b][m][n] = (f32x4){0.f, 0.f, 0.f, 0.f};
;     bf16x8 At[4][2], B0[2][2], B1[2][2];
;     const char* cA = (const char*)g.A + (size_t)cur.pm * tstep; const char* cB = (const char*)g.Bt + (size_t)cur.pn * tstep;
;     if constexpr (SP2) {
;         PG8_STAGE(PG8_SB(0, 0), cB, voffB); PG8_STAGE(PG8_SB(0, 1), cB + hstep, voffB);
;         S.a_ready(cur);
;         PG8_STAGE(PG8_SA(0, 0), cA, voffA); PG8_STAGE(PG8_SA(0, 1), cA + hstep, voffA);
;         if (wr == 1) PG8_BAR;
;         PG8_WAIT_V(2); PG8_BAR;
;         PG8_STAGE(PG8_SB(1, 0), cB + kstep, voffB); PG8_STAGE(PG8_SA(1, 0), cA + kstep, voffA); PG8_STAGE(PG8_SB(1, 1), cB + hstep + kstep, voffB);
; __global__ void __launch_bounds__(NWAVES * 64, 2) mk_fwd(Args args) {
;     ...
;     if (IN(14)) { pg8::Gemm g{PB + (size_t)MROWS * PLE, (const bf16*)(ws + WS_WP1), MROWS, DM, kple, kple}; ORDER(S, NT, 3 * U_WO + U_UP + U_CONV, nullptr, 0u, nullptr);
.LBB0_1358:
	s_cmp_gt_i32 s58, 14
	s_cselect_b64 s[0:1], -1, 0
	s_cmp_lt_i32 s59, 15
	s_cselect_b64 s[2:3], -1, 0
	s_or_b64 s[0:1], s[0:1], s[2:3]
	s_and_b64 vcc, exec, s[0:1]
	v_readlane_b32 s19, v249, 5
	s_cbranch_vccnz .LBB0_1450
	s_add_u32 s8, s22, 0x2f900000
	s_addc_u32 s9, s23, 0
	s_abs_i32 s0, s19
	v_cvt_f32_u32_e32 v0, s0
	s_sub_i32 s3, 0, s0
	v_readlane_b32 s1, v250, 58
	s_addk_i32 s1, 0xf640
	v_rcp_iflag_f32_e32 v0, v0
	s_ashr_i32 s2, s1, 31
	s_abs_i32 s1, s1
	v_mbcnt_hi_u32_b32 v144, -1, v234
	v_mul_f32_e32 v0, 0x4f7ffffe, v0
	v_cvt_u32_f32_e32 v0, v0
	v_mov_b32_e32 v1, v144
	v_readfirstlane_b32 s4, v0
	s_mul_i32 s3, s3, s4
	s_mul_hi_u32 s3, s4, s3
	s_add_i32 s4, s4, s3
	s_mul_hi_u32 s3, s1, s4
	s_mul_i32 s3, s3, s0
	s_sub_i32 s1, s1, s3
	s_sub_i32 s3, s1, s0
	s_cmp_ge_u32 s1, s0
	s_cselect_b32 s1, s3, s1
	s_sub_i32 s3, s1, s0
	s_cmp_ge_u32 s1, s0
	s_cselect_b32 s1, s3, s1
	s_xor_b32 s1, s1, s2
	s_sub_i32 s1, s1, s2
	s_add_i32 s1, s1, s19
	s_ashr_i32 s2, s1, 31
	s_abs_i32 s1, s1
	s_mul_hi_u32 s3, s1, s4
	s_mul_i32 s3, s3, s0
	s_sub_i32 s1, s1, s3
	s_sub_i32 s3, s1, s0
	s_cmp_ge_u32 s1, s0
	s_cselect_b32 s1, s3, s1
	s_sub_i32 s3, s1, s0
	s_cmp_ge_u32 s1, s0
	s_cselect_b32 s0, s3, s1
	v_readlane_b32 s1, v250, 8
	s_xor_b32 s0, s0, s2
	s_sub_i32 s77, s0, s2
	s_lshl_b32 s0, s1, 5
	s_lshr_b32 s61, s63, 8
	s_and_b32 s33, s0, 0x60
	s_lshl_b32 s76, s1, 10
	s_lshl_b32 s60, s61, 6
	s_lshl_b32 s59, s61, 13
	s_lshr_b32 s58, s33, 3
	s_cmpk_lt_i32 s77, 0x120
	s_cselect_b64 s[2:3], -1, 0
	s_cmpk_gt_i32 s77, 0x11f
	s_cbranch_scc1 .LBB0_1380
	v_lshl_add_u32 v0, v1, 4, s76
	v_add_u32_e32 v2, 0x2000, v0
	v_ashrrev_i32_e32 v3, 31, v2
	v_lshrrev_b32_e32 v3, 22, v3
	v_add_u32_e32 v3, v2, v3
	v_ashrrev_i32_e32 v3, 10, v3
	v_mul_i32_i24_e32 v4, 0x400, v3
	v_sub_u32_e32 v2, v2, v4
	v_lshrrev_b32_e32 v4, 4, v2
	v_bitop3_b32 v2, v4, v2, 32 bitop3:0x6c
	v_ashrrev_i32_e32 v4, 31, v2
	v_lshrrev_b32_e32 v4, 26, v4
	v_add_u32_e32 v4, v2, v4
	v_lshlrev_b32_e32 v6, 3, v3
	v_lshlrev_b32_e32 v3, 5, v3
	v_and_b32_e32 v14, 32, v3
	v_and_b32_e32 v3, 0xffc0, v4
	v_sub_u32_e32 v2, v2, v3
	v_ashrrev_i32_e32 v5, 6, v4
	v_and_b32_e32 v6, -16, v6
	v_lshrrev_b16_e32 v3, 7, v2
	v_add_u32_e32 v6, v5, v6
	v_and_b32_e32 v3, 1, v3
	v_and_b32_e32 v5, 3, v5
	s_mov_b32 s0, 0x7fffffe0
	v_lshrrev_b32_e32 v7, 2, v6
	v_lshlrev_b32_e32 v8, 1, v6
	v_add_u16_e32 v2, v2, v3
	v_mov_b32_e32 v3, 1
	v_and_or_b32 v5, v6, s0, v5
	v_and_b32_e32 v7, 4, v7
	v_and_b32_e32 v8, 24, v8
	v_ashrrev_i16_sdwa v2, v3, sext(v2) dst_sel:DWORD dst_unused:UNUSED_PAD src0_sel:DWORD src1_sel:BYTE_0
	v_readlane_b32 s18, v249, 17
	v_or3_b32 v5, v5, v7, v8
	v_bfe_i32 v15, v2, 0, 16
	v_mul_lo_u32 v5, v5, s18
	v_add_u32_e32 v2, v14, v15
	s_waitcnt vmcnt(0)
	v_mul_lo_u32 v16, v6, s18
	v_add_lshl_u32 v132, v5, v2, 1
	v_add_lshl_u32 v134, v2, v16, 1
	v_ashrrev_i32_e32 v2, 31, v0
	v_lshrrev_b32_e32 v2, 22, v2
	v_add_u32_e32 v2, v0, v2
	v_ashrrev_i32_e32 v2, 10, v2
	v_mul_i32_i24_e32 v4, 0x400, v2
	v_sub_u32_e32 v0, v0, v4
	v_lshrrev_b32_e32 v4, 4, v0
	v_bitop3_b32 v0, v4, v0, 32 bitop3:0x6c
	v_ashrrev_i32_e32 v4, 31, v0
	v_lshrrev_b32_e32 v4, 26, v4
	s_add_u32 s62, s22, 0x32180000
	v_add_u32_e32 v4, v0, v4
	v_lshlrev_b32_e32 v6, 3, v2
	s_addc_u32 s63, s23, 0
	v_ashrrev_i32_e32 v5, 6, v4
	v_and_b32_e32 v6, -16, v6
	s_add_u32 s64, s22, 0xd100000
	v_add_u32_e32 v6, v5, v6
	v_and_b32_e32 v5, 3, v5
	s_addc_u32 s65, s23, 0
	v_and_or_b32 v5, v6, s0, v5
	s_ashr_i32 s0, s77, 31
	s_lshr_b32 s0, s0, 27
	s_add_i32 s0, s77, s0
	s_and_b32 s1, s0, 0xffffffe0
	v_readlane_b32 s19, v249, 18
	s_sub_i32 s1, s77, s1
	s_ashr_i32 s0, s0, 5
	s_ashr_i32 s19, s18, 31
	s_lshl_b32 s10, s0, 2
	s_and_b32 s11, s1, 3
	s_lshl_b64 s[6:7], s[18:19], 9
	s_or_b32 s68, s11, s10
	s_ashr_i32 s0, s0, 31
	s_ashr_i32 s67, s1, 2
	s_mul_hi_u32 s1, s6, s68
	s_mul_i32 s0, s6, s0
	s_add_i32 s10, s1, s0
	s_lshr_b64 s[0:1], s[18:19], 23
	s_mul_i32 s1, s0, s68
	v_lshlrev_b32_e32 v2, 5, v2
	s_add_i32 s12, s10, s1
	s_ashr_i32 s1, s67, 31
	v_and_b32_e32 v17, 32, v2
	v_and_b32_e32 v2, 0xc0, v4
	s_mul_hi_u32 s10, s6, s67
	s_mul_i32 s1, s6, s1
	v_lshrrev_b32_e32 v7, 2, v6
	v_lshlrev_b32_e32 v8, 1, v6
	v_sub_u32_e32 v0, v0, v2
	s_add_i32 s1, s10, s1
	s_mul_i32 s0, s0, s67
	s_lshl_b64 s[4:5], s[18:19], 8
	v_and_b32_e32 v7, 4, v7
	v_and_b32_e32 v8, 24, v8
	v_ashrrev_i16_sdwa v0, v3, sext(v0) dst_sel:DWORD dst_unused:UNUSED_PAD src0_sel:DWORD src1_sel:BYTE_0
	s_add_i32 s1, s1, s0
	s_mul_i32 s0, s6, s67
	v_or3_b32 v5, v5, v7, v8
	v_bfe_i32 v18, v0, 0, 16
	s_add_u32 s10, s64, s0
	v_mul_lo_u32 v5, v5, s18
	v_add_u32_e32 v0, v17, v18
	s_addc_u32 s11, s65, s1
	s_add_i32 s66, s76, 0
	v_add_lshl_u32 v136, v5, v0, 1
	s_add_i32 m0, s66, 0x10000
	s_mul_i32 s13, s6, s68
	global_load_lds_dwordx4 v136, s[10:11]
	s_add_i32 m0, s66, 0x12000
	s_add_u32 s0, s10, s4
	global_load_lds_dwordx4 v132, s[10:11]
	s_addc_u32 s1, s11, s5
	s_add_i32 m0, s66, 0x14000
	v_mul_lo_u32 v19, v6, s18
	global_load_lds_dwordx4 v136, s[0:1]
	s_add_i32 m0, s66, 0x16000
	s_add_u32 s14, s62, s13
	s_addc_u32 s15, s63, s12
	s_add_i32 s69, s66, 0x2000
	v_add_lshl_u32 v138, v0, v19, 1
	global_load_lds_dwordx4 v132, s[0:1]
	s_mov_b32 m0, s66
	s_add_u32 s12, s14, s4
	global_load_lds_dwordx4 v138, s[14:15]
	s_mov_b32 m0, s69
	s_addc_u32 s13, s15, s5
	s_add_i32 s70, s66, 0x4000
	global_load_lds_dwordx4 v134, s[14:15]
	s_mov_b32 m0, s70
	s_add_i32 s71, s66, 0x6000
	global_load_lds_dwordx4 v138, s[12:13]
	s_mov_b32 m0, s71
	v_mov_b32_e32 v0, 0
	global_load_lds_dwordx4 v134, s[12:13]
	v_mov_b32_e32 v137, v0
	v_mov_b32_e32 v133, v0
	v_mov_b32_e32 v139, v0
	v_mov_b32_e32 v135, v0
	s_cmp_eq_u32 s61, 1
	v_lshl_add_u64 v[10:11], s[10:11], 0, v[136:137]
	v_lshl_add_u64 v[6:7], s[10:11], 0, v[132:133]
	v_lshl_add_u64 v[4:5], s[0:1], 0, v[136:137]
	v_lshl_add_u64 v[2:3], s[0:1], 0, v[132:133]
	v_lshl_add_u64 v[8:9], s[14:15], 0, v[138:139]
	s_cselect_b64 s[12:13], -1, 0
	s_cmp_lg_u32 s61, 1
	v_lshl_add_u64 v[12:13], s[14:15], 0, v[134:135]
	s_cbranch_scc1 .LBB0_1362
	s_barrier

; #define GAS __attribute__((address_space(1)))
; __device__ __forceinline__ void final_chain_phase(const float* H, const float* ss, const float* gf, float* out, const unsigned* ready, unsigned need, unsigned* tmo, int crot, int G, int wave) {
;     int lane = (int)__builtin_amdgcn_mbcnt_hi(~0u, __builtin_amdgcn_mbcnt_lo(~0u, 0u)); asm volatile("" : "+v"(lane));
;     f32x4 gq[8];
; #pragma unroll
;     for (int j = 0; j < 8; ++j) gq[j] = *((const GAS f32x4*)gf + lane + 64 * j);
;     for (int l = crot; l < (MROWS / 256) * 8; l += G) {
;         const int pm = l >> 3, slab = l & 7;
;         if (wave == 0) {
;             const unsigned long long t0 = __builtin_amdgcn_s_memrealtime(); unsigned polls = 0;
;             while ((unsigned)__builtin_amdgcn_readfirstlane(__hip_atomic_load(ready + 64 * pm, __ATOMIC_RELAXED, __HIP_MEMORY_SCOPE_AGENT)) < need) {
;                 if ((++polls & 255u) == 0u && __builtin_amdgcn_readfirstlane(__hip_atomic_load(tmo, __ATOMIC_RELAXED, __HIP_MEMORY_SCOPE_AGENT)) != 0u) break;
;                 if (__builtin_amdgcn_s_memrealtime() - t0 > 2000000ull) { __hip_atomic_store(tmo, 1u, __ATOMIC_RELAXED, __HIP_MEMORY_SCOPE_AGENT); break; }
;                 __builtin_amdgcn_s_sleep(2); }
;             __builtin_amdgcn_fence(__ATOMIC_ACQUIRE, "agent");
;             asm volatile("s_waitcnt vmcnt(0)" ::: "memory");
;         }
;         __syncthreads();
; __global__ void __launch_bounds__(NWAVES * 64, 2) mk_fwd(Args args) {
;     ...
;     if (IN(15)) final_chain_phase(H, ssb + SS_FIN * MROWS, args.in[I_GFIN], out + OUT_Y, CNT(9), 8u * NT, tmo, ROT(4 * U_WO + U_UP + U_CONV), G, wave);
.LBB0_1450:
	v_readlane_b32 s2, v250, 59
	v_readlane_b32 s3, v250, 60
	s_cmp_gt_i32 s2, 15
	s_cselect_b64 s[0:1], -1, 0
	s_cmp_lt_i32 s3, 16
	s_cselect_b64 s[2:3], -1, 0
	s_or_b64 s[0:1], s[0:1], s[2:3]
	s_and_b64 vcc, exec, s[0:1]
	s_cbranch_vccnz .LBB0_1467
	s_abs_i32 s0, s19
	v_cvt_f32_u32_e32 v0, s0
	s_sub_i32 s3, 0, s0
	v_readlane_b32 s1, v250, 58
	s_addk_i32 s1, 0xf520
	v_rcp_iflag_f32_e32 v0, v0
	s_ashr_i32 s2, s1, 31
	s_abs_i32 s1, s1
	v_mul_f32_e32 v0, 0x4f7ffffe, v0
	v_cvt_u32_f32_e32 v0, v0
	s_nop 0
	v_readfirstlane_b32 s4, v0
	s_mul_i32 s3, s3, s4
	s_mul_hi_u32 s3, s4, s3
	s_add_i32 s4, s4, s3
	s_mul_hi_u32 s3, s1, s4
	s_mul_i32 s3, s3, s0
	s_sub_i32 s1, s1, s3
	s_sub_i32 s3, s1, s0
	s_cmp_ge_u32 s1, s0
	s_cselect_b32 s1, s3, s1
	s_sub_i32 s3, s1, s0
	s_cmp_ge_u32 s1, s0
	s_cselect_b32 s1, s3, s1
	s_xor_b32 s1, s1, s2
	s_sub_i32 s1, s1, s2
	s_add_i32 s1, s1, s19
	s_ashr_i32 s2, s1, 31
	s_abs_i32 s1, s1
	s_mul_hi_u32 s3, s1, s4
	s_mul_i32 s3, s3, s0
	s_sub_i32 s1, s1, s3
	s_sub_i32 s3, s1, s0
	s_cmp_ge_u32 s1, s0
	s_cselect_b32 s1, s3, s1
	s_sub_i32 s3, s1, s0
	s_cmp_ge_u32 s1, s0
	s_cselect_b32 s0, s3, s1
	s_xor_b32 s0, s0, s2
	s_sub_i32 s10, s0, s2
	v_mbcnt_hi_u32_b32 v0, -1, v234
	s_cmpk_gt_i32 s10, 0x11f
	s_cbranch_scc1 .LBB0_1467
	v_ashrrev_i32_e32 v1, 31, v0
	v_readlane_b32 s36, v250, 25
	s_waitcnt vmcnt(0)
	v_lshlrev_b64 v[34:35], 4, v[0:1]
	v_readlane_b32 s50, v250, 39
	v_readlane_b32 s51, v250, 40
	s_add_u32 s11, s22, 0x13f000
	s_addc_u32 s12, s23, 0
	v_lshl_add_u64 v[16:17], s[50:51], 0, v[34:35]
	v_add_co_u32_e32 v32, vcc, 0x1000, v16
	global_load_dwordx4 v[0:3], v[16:17], off
	global_load_dwordx4 v[4:7], v[16:17], off offset:1024
	global_load_dwordx4 v[8:11], v[16:17], off offset:2048
	global_load_dwordx4 v[12:15], v[16:17], off offset:3072
	v_addc_co_u32_e32 v33, vcc, 0, v17, vcc
	global_load_dwordx4 v[16:19], v[32:33], off
	global_load_dwordx4 v[20:23], v[32:33], off offset:1024
	global_load_dwordx4 v[24:27], v[32:33], off offset:2048
	global_load_dwordx4 v[28:31], v[32:33], off offset:3072
	s_add_u32 s13, s22, 0x34000
	s_addc_u32 s14, s23, 0
	s_cmp_lt_u32 s63, 64
	v_readlane_b32 s2, v250, 8
	s_cselect_b64 s[0:1], -1, 0
	s_lshl_b32 s16, s2, 2
	v_readlane_b32 s2, v249, 1
	v_readlane_b32 s3, v249, 2
	v_cndmask_b32_e64 v36, 0, 1, s[0:1]
	s_movk_i32 s15, 0x1000
	v_lshl_add_u64 v[32:33], s[2:3], 0, v[34:35]
	v_lshl_add_u64 v[34:35], s[20:21], 0, v[34:35]
	v_cmp_ne_u32_e64 s[0:1], 1, v36
	v_mov_b32_e32 v38, 0
	v_mov_b32_e32 v39, 1
	v_mov_b32_e32 v40, 0x358637bd
	v_mov_b64_e32 v[36:37], 0x1e8481
	v_readlane_b32 s37, v250, 26
	v_readlane_b32 s38, v250, 27
	v_readlane_b32 s39, v250, 28
	v_readlane_b32 s40, v250, 29
	v_readlane_b32 s41, v250, 30
	v_readlane_b32 s42, v250, 31
	v_readlane_b32 s43, v250, 32
	v_readlane_b32 s44, v250, 33
	v_readlane_b32 s45, v250, 34
	v_readlane_b32 s46, v250, 35
	v_readlane_b32 s47, v250, 36
	v_readlane_b32 s48, v250, 37
	v_readlane_b32 s49, v250, 38
	s_branch .LBB0_1455
